# XCD-local barrier mode additionally requires the 256-workgroup grid (the row/tile-to-XCD mappings it relies on are the G==256 fast paths); otherwise full barriers
# speedup vs baseline: 1.0008x; 1.0008x over previous
_Z10fwd_kernel6Params:
	s_mov_b64 s[94:95], s[0:1]
	s_mov_b32 s100, 0
	s_mov_b32 s101, 0
	s_load_dwordx4 s[44:47], s[0:1], 0xc8
	s_load_dword s48, s[0:1], 0xd8
	s_add_u32 s0, s94, 0xd8
	s_addc_u32 s1, s95, 0
	v_readfirstlane_b32 s33, v0
	v_writelane_b32 v251, s0, 0
	v_cmp_gt_u32_e32 vcc, 64, v0
	s_nop 0
	v_writelane_b32 v251, s1, 1
	s_and_saveexec_b64 s[0:1], vcc
	v_lshl_add_u32 v1, v0, 2, 0
	v_add_u32_e32 v1, 0x27c00, v1
	v_mov_b32_e32 v2, 0
	ds_write_b32 v1, v2
	s_or_b64 exec, exec, s[0:1]
	s_waitcnt lgkmcnt(0)
	s_barrier
	s_getreg_b32 s3, hwreg(HW_REG_XCC_ID, 0, 4)
	s_mov_b32 s11, 0
	v_cmp_eq_u32_e32 vcc, 0, v0
	s_and_saveexec_b64 s[0:1], vcc
	s_cbranch_execz .LBB0_5
	s_mov_b64 s[4:5], exec
	v_mbcnt_lo_u32_b32 v0, s4, 0
	v_mbcnt_hi_u32_b32 v0, s5, v0
	v_cmp_eq_u32_e32 vcc, 0, v0
	s_and_b64 s[6:7], exec, vcc
	s_mov_b64 exec, s[6:7]
	s_cbranch_execz .LBB0_5
	s_lshl_b32 s3, s3, 8
	s_and_b32 s3, s3, 0xf00
	s_bcnt1_i32_b64 s4, s[4:5]
	v_mov_b32_e32 v0, s3
	v_mov_b32_e32 v1, s4
	global_atomic_add v0, v1, s[46:47] offset:1024
	s_lshr_b32 s6, s3, 8
	s_and_b32 s7, s2, 7
	s_cmp_lg_u32 s6, s7
	s_cbranch_scc1 .Lmm_report
	s_cmpk_eq_u32 s48, 0x100
	s_cbranch_scc1 .LBB0_5
.Lmm_report:
	v_mov_b32_e32 v0, 0x280
	global_atomic_add v0, v1, s[46:47]
